# v67 (P7 K=32 MFMAs + scalar Horner + relaxed waits) + s_setprio 1/0 around the P7 MFMA block
# speedup vs baseline: 1.0030x; 1.0030x over previous
; template <int DIR>
; __device__ __forceinline__ void s5_local_dir(const bf16_t* UZ, unsigned char* ws, int gw, int NGW, int lane) {
;     ...
;     for (int c = c0; c < c1; ++c) {
;         bf16x4 Uf[4];
; #pragma unroll
;         for (int m = 0; m < 4; ++m) Uf[m] = Un[m];
;         if (c + 1 < c1) load_uf(Un, UZ, chunk_rowbase(b, DIR, c + 1), g, lane);
;         float* e = ebase + (size_t)c * 128;
; #pragma unroll
;         for (int t = 0; t < 4; ++t) {
;             f32x4 cr = {0.f, 0.f, 0.f, 0.f}, ci = {0.f, 0.f, 0.f, 0.f};
; #pragma unroll
;             for (int m = 0; m < 4; ++m) {
;                 cr = __builtin_amdgcn_mfma_f32_16x16x16bf16_1k(Uf[m], Bre[m][t], cr, 0, 0, 0);
;                 ci = __builtin_amdgcn_mfma_f32_16x16x16bf16_1k(Uf[m], Bim[m][t], ci, 0, 0, 0);
;             }
;             f32x2 s2 = {DIR ? cr[3] : cr[0], DIR ? ci[3] : ci[0]};
; #pragma unroll
;             for (int ii = 1; ii < 4; ++ii) { const int i = DIR ? 3 - ii : ii;
;                 s2 = cmac(s2, (f32x2){a1r[t], a1r[t]}, (f32x2){-a1i[t], a1i[t]}, (f32x2){cr[i], ci[i]}); }
;             s2 = cmac(s2, (f32x2){wr_[t], wr_[t]}, (f32x2){-wi_[t], wi_[t]}, (f32x2){0.f, 0.f});
;             float sr = s2.x, si = s2.y;
;             sr += __shfl_xor(sr, 16); si += __shfl_xor(si, 16); sr += __shfl_xor(sr, 32); si += __shfl_xor(si, 32);
;             if (fq == 0) { e[16 * t + fr] = Rr[t]; e[64 + 16 * t + fr] = Ri[t]; }
;             const float nr = fmaf(a64r[t], Rr[t], fmaf(-a64i[t], Ri[t], sr)), ni = fmaf(a64r[t], Ri[t], fmaf(a64i[t], Rr[t], si)); Rr[t] = nr; Ri[t] = ni;
;         }
.LBB0_652:
	global_store_dword v[116:117], v240, off offset:-256
	global_store_dword v[116:117], v241, off
	s_waitcnt vmcnt(9)
	s_setprio 1
	v_mfma_f32_16x16x32_bf16 v[140:143], v[108:111], v[26:29], 0
	v_mfma_f32_16x16x32_bf16 v[144:147], v[108:111], v[34:37], 0
	v_mfma_f32_16x16x32_bf16 v[196:199], v[108:111], v[48:51], 0
	v_mfma_f32_16x16x32_bf16 v[200:203], v[108:111], v[56:59], 0
	v_mfma_f32_16x16x32_bf16 v[208:211], v[108:111], v[70:73], 0
	v_mfma_f32_16x16x32_bf16 v[212:215], v[108:111], v[78:81], 0
	v_mfma_f32_16x16x32_bf16 v[228:231], v[108:111], v[92:95], 0
	v_mfma_f32_16x16x32_bf16 v[184:187], v[108:111], v[100:103], 0
	v_mfma_f32_16x16x32_bf16 v[140:143], v[112:115], v[30:33], v[140:143]
	v_mfma_f32_16x16x32_bf16 v[144:147], v[112:115], v[38:41], v[144:147]
	v_mfma_f32_16x16x32_bf16 v[196:199], v[112:115], v[52:55], v[196:199]
	v_mfma_f32_16x16x32_bf16 v[200:203], v[112:115], v[60:63], v[200:203]
	v_mfma_f32_16x16x32_bf16 v[208:211], v[112:115], v[74:77], v[208:211]
	v_mfma_f32_16x16x32_bf16 v[212:215], v[112:115], v[82:85], v[212:215]
	v_mfma_f32_16x16x32_bf16 v[228:231], v[112:115], v[96:99], v[228:231]
	v_mfma_f32_16x16x32_bf16 v[184:187], v[112:115], v[104:107], v[184:187]
	s_setprio 0
	s_nop 6
	v_fma_f32 v142, v20, v143, v142
	v_fma_f32 v198, v42, v199, v198
	v_fma_f32 v210, v64, v211, v210
	v_fma_f32 v230, v86, v231, v230
	v_fma_f32 v146, v21, v147, v146
	v_fma_f32 v202, v43, v203, v202
	v_fma_f32 v214, v65, v215, v214
	v_fma_f32 v186, v87, v187, v186
	v_fma_f32 v142, v0, v147, v142
	v_fma_f32 v198, v4, v203, v198
	v_fma_f32 v210, v8, v215, v210
	v_fma_f32 v230, v12, v187, v230
	v_fma_f32 v146, v1, v143, v146
	v_fma_f32 v202, v5, v199, v202
	v_fma_f32 v214, v9, v211, v214
	v_fma_f32 v186, v13, v231, v186
	v_fma_f32 v141, v20, v142, v141
	v_fma_f32 v197, v42, v198, v197
	v_fma_f32 v209, v64, v210, v209
	v_fma_f32 v229, v86, v230, v229
	v_fma_f32 v145, v21, v146, v145
	v_fma_f32 v201, v43, v202, v201
	v_fma_f32 v213, v65, v214, v213
	v_fma_f32 v185, v87, v186, v185
	v_fma_f32 v141, v0, v146, v141
	v_fma_f32 v197, v4, v202, v197
	v_fma_f32 v209, v8, v214, v209
	v_fma_f32 v229, v12, v186, v229
	v_fma_f32 v145, v1, v142, v145
	v_fma_f32 v201, v5, v198, v201
	v_fma_f32 v213, v9, v210, v213
	v_fma_f32 v185, v13, v230, v185
	v_fma_f32 v140, v20, v141, v140
	v_fma_f32 v196, v42, v197, v196
	v_fma_f32 v208, v64, v209, v208
	v_fma_f32 v228, v86, v229, v228
	v_fma_f32 v144, v21, v145, v144
	v_fma_f32 v200, v43, v201, v200
	v_fma_f32 v212, v65, v213, v212
	v_fma_f32 v184, v87, v185, v184
	v_fma_f32 v140, v0, v145, v140
	v_fma_f32 v196, v4, v201, v196
	v_fma_f32 v208, v8, v213, v208
	v_fma_f32 v228, v12, v185, v228
	v_fma_f32 v144, v1, v141, v144
	v_fma_f32 v200, v5, v197, v200
	v_fma_f32 v212, v9, v209, v212
	v_fma_f32 v184, v13, v229, v184
	v_mul_f32_e32 v142, v22, v140
	v_mul_f32_e32 v198, v44, v196
	v_mul_f32_e32 v210, v66, v208
	v_mul_f32_e32 v229, v88, v228
	v_mul_f32_e32 v141, v23, v144
	v_mul_f32_e32 v197, v45, v200
	v_mul_f32_e32 v209, v67, v212
	v_mul_f32_e32 v230, v89, v184
	v_fma_f32 v141, v25, v140, v141
	v_fma_f32 v197, v47, v196, v197
	v_fma_f32 v209, v69, v208, v209
	v_fma_f32 v185, v91, v228, v230
	v_fma_f32 v140, v24, v144, v142
	v_fma_f32 v196, v46, v200, v198
	v_fma_f32 v208, v68, v212, v210
	v_fma_f32 v184, v90, v184, v229
	s_nop 1
	v_permlane32_swap_b32_e32 v140, v208
	v_permlane32_swap_b32_e32 v141, v209
	v_permlane32_swap_b32_e32 v196, v184
	v_permlane32_swap_b32_e32 v197, v185
	v_add_f32_e32 v140, v140, v208
	v_add_f32_e32 v196, v196, v184
	v_add_f32_e32 v141, v141, v209
	v_add_f32_e32 v197, v197, v185
	s_nop 0
	v_permlane16_swap_b32_e32 v140, v196
	v_permlane16_swap_b32_e32 v141, v197
	v_add_f32_e32 v140, v140, v196
	v_add_f32_e32 v141, v141, v197
	v_fma_f32 v244, -v243, v241, v140
	v_fma_f32 v245, v243, v240, v141
	v_fma_f32 v240, v242, v240, v244
	v_fma_f32 v241, v242, v241, v245
	v_lshl_add_u64 v[116:117], v[116:117], 0, s[2:3]
	v_subrev_u32_e32 v16, 64, v16
	s_and_b64 vcc, exec, s[36:37]
	s_cbranch_vccnz .LBB0_684
	s_mov_b32 s38, s49
	s_waitcnt vmcnt(5)
	v_mov_b32_e32 v110, v118
	v_mov_b32_e32 v111, v119
	s_waitcnt vmcnt(4)
	v_mov_b32_e32 v112, v120
	v_mov_b32_e32 v113, v121
	s_waitcnt vmcnt(3)
	v_mov_b32_e32 v114, v122
	v_mov_b32_e32 v115, v123
	s_waitcnt vmcnt(2)
	v_mov_b32_e32 v108, v124
	v_mov_b32_e32 v109, v125
	s_branch .LBB0_649

; template <int DIR>
; __device__ __forceinline__ void s5_local_dir(const bf16_t* UZ, unsigned char* ws, int gw, int NGW, int lane) {
;     ...
;     for (int c = c0; c < c1; ++c) {
;         bf16x4 Uf[4];
; #pragma unroll
;         for (int m = 0; m < 4; ++m) Uf[m] = Un[m];
;         if (c + 1 < c1) load_uf(Un, UZ, chunk_rowbase(b, DIR, c + 1), g, lane);
;         float* e = ebase + (size_t)c * 128;
; #pragma unroll
;         for (int t = 0; t < 4; ++t) {
;             f32x4 cr = {0.f, 0.f, 0.f, 0.f}, ci = {0.f, 0.f, 0.f, 0.f};
; #pragma unroll
;             for (int m = 0; m < 4; ++m) {
;                 cr = __builtin_amdgcn_mfma_f32_16x16x16bf16_1k(Uf[m], Bre[m][t], cr, 0, 0, 0);
;                 ci = __builtin_amdgcn_mfma_f32_16x16x16bf16_1k(Uf[m], Bim[m][t], ci, 0, 0, 0);
;             }
;             f32x2 s2 = {DIR ? cr[3] : cr[0], DIR ? ci[3] : ci[0]};
; #pragma unroll
;             for (int ii = 1; ii < 4; ++ii) { const int i = DIR ? 3 - ii : ii;
;                 s2 = cmac(s2, (f32x2){a1r[t], a1r[t]}, (f32x2){-a1i[t], a1i[t]}, (f32x2){cr[i], ci[i]}); }
;             s2 = cmac(s2, (f32x2){wr_[t], wr_[t]}, (f32x2){-wi_[t], wi_[t]}, (f32x2){0.f, 0.f});
;             float sr = s2.x, si = s2.y;
;             sr += __shfl_xor(sr, 16); si += __shfl_xor(si, 16); sr += __shfl_xor(sr, 32); si += __shfl_xor(si, 32);
;             if (fq == 0) { e[16 * t + fr] = Rr[t]; e[64 + 16 * t + fr] = Ri[t]; }
;             const float nr = fmaf(a64r[t], Rr[t], fmaf(-a64i[t], Ri[t], sr)), ni = fmaf(a64r[t], Ri[t], fmaf(a64i[t], Rr[t], si)); Rr[t] = nr; Ri[t] = ni;
;         }
.LBB0_674:
	global_store_dword v[116:117], v240, off offset:-256
	global_store_dword v[116:117], v241, off
	s_waitcnt vmcnt(9)
	s_setprio 1
	v_mfma_f32_16x16x32_bf16 v[136:139], v[108:111], v[26:29], 0
	v_mfma_f32_16x16x32_bf16 v[140:143], v[108:111], v[34:37], 0
	v_mfma_f32_16x16x32_bf16 v[196:199], v[108:111], v[48:51], 0
	v_mfma_f32_16x16x32_bf16 v[200:203], v[108:111], v[56:59], 0
	v_mfma_f32_16x16x32_bf16 v[208:211], v[108:111], v[70:73], 0
	v_mfma_f32_16x16x32_bf16 v[212:215], v[108:111], v[78:81], 0
	v_mfma_f32_16x16x32_bf16 v[224:227], v[108:111], v[88:91], 0
	v_mfma_f32_16x16x32_bf16 v[184:187], v[108:111], v[100:103], 0
	v_mfma_f32_16x16x32_bf16 v[136:139], v[112:115], v[30:33], v[136:139]
	v_mfma_f32_16x16x32_bf16 v[140:143], v[112:115], v[38:41], v[140:143]
	v_mfma_f32_16x16x32_bf16 v[196:199], v[112:115], v[52:55], v[196:199]
	v_mfma_f32_16x16x32_bf16 v[200:203], v[112:115], v[60:63], v[200:203]
	v_mfma_f32_16x16x32_bf16 v[208:211], v[112:115], v[74:77], v[208:211]
	v_mfma_f32_16x16x32_bf16 v[212:215], v[112:115], v[82:85], v[212:215]
	v_mfma_f32_16x16x32_bf16 v[224:227], v[112:115], v[96:99], v[224:227]
	v_mfma_f32_16x16x32_bf16 v[184:187], v[112:115], v[104:107], v[184:187]
	s_setprio 0
	s_nop 6
	v_fma_f32 v137, v18, v136, v137
	v_fma_f32 v197, v42, v196, v197
	v_fma_f32 v209, v64, v208, v209
	v_fma_f32 v225, v86, v224, v225
	v_fma_f32 v141, v19, v140, v141
	v_fma_f32 v201, v43, v200, v201
	v_fma_f32 v213, v65, v212, v213
	v_fma_f32 v185, v87, v184, v185
	v_fma_f32 v137, v0, v140, v137
	v_fma_f32 v197, v4, v200, v197
	v_fma_f32 v209, v8, v212, v209
	v_fma_f32 v225, v12, v184, v225
	v_fma_f32 v141, v1, v136, v141
	v_fma_f32 v201, v5, v196, v201
	v_fma_f32 v213, v9, v208, v213
	v_fma_f32 v185, v13, v224, v185
	v_fma_f32 v138, v18, v137, v138
	v_fma_f32 v198, v42, v197, v198
	v_fma_f32 v210, v64, v209, v210
	v_fma_f32 v226, v86, v225, v226
	v_fma_f32 v142, v19, v141, v142
	v_fma_f32 v202, v43, v201, v202
	v_fma_f32 v214, v65, v213, v214
	v_fma_f32 v186, v87, v185, v186
	v_fma_f32 v138, v0, v141, v138
	v_fma_f32 v198, v4, v201, v198
	v_fma_f32 v210, v8, v213, v210
	v_fma_f32 v226, v12, v185, v226
	v_fma_f32 v142, v1, v137, v142
	v_fma_f32 v202, v5, v197, v202
	v_fma_f32 v214, v9, v209, v214
	v_fma_f32 v186, v13, v225, v186
	v_fma_f32 v139, v18, v138, v139
	v_fma_f32 v199, v42, v198, v199
	v_fma_f32 v211, v64, v210, v211
	v_fma_f32 v227, v86, v226, v227
	v_fma_f32 v143, v19, v142, v143
	v_fma_f32 v203, v43, v202, v203
	v_fma_f32 v215, v65, v214, v215
	v_fma_f32 v187, v87, v186, v187
	v_fma_f32 v139, v0, v142, v139
	v_fma_f32 v199, v4, v202, v199
	v_fma_f32 v211, v8, v214, v211
	v_fma_f32 v227, v12, v186, v227
	v_fma_f32 v143, v1, v138, v143
	v_fma_f32 v203, v5, v198, v203
	v_fma_f32 v215, v9, v210, v215
	v_fma_f32 v187, v13, v226, v187
	v_mul_f32_e32 v136, v22, v139
	v_mul_f32_e32 v196, v44, v199
	v_mul_f32_e32 v208, v66, v211
	v_mul_f32_e32 v224, v92, v227
	v_mul_f32_e32 v137, v23, v143
	v_mul_f32_e32 v197, v45, v203
	v_mul_f32_e32 v209, v67, v215
	v_mul_f32_e32 v225, v93, v187
	v_fma_f32 v137, v25, v139, v137
	v_fma_f32 v197, v47, v199, v197
	v_fma_f32 v209, v69, v211, v209
	v_fma_f32 v185, v95, v227, v225
	v_fma_f32 v136, v24, v143, v136
	v_fma_f32 v196, v46, v203, v196
	v_fma_f32 v208, v68, v215, v208
	v_fma_f32 v184, v94, v187, v224
	s_nop 1
	v_permlane32_swap_b32_e32 v136, v208
	v_permlane32_swap_b32_e32 v137, v209
	v_permlane32_swap_b32_e32 v196, v184
	v_permlane32_swap_b32_e32 v197, v185
	v_add_f32_e32 v136, v136, v208
	v_add_f32_e32 v196, v196, v184
	v_add_f32_e32 v137, v137, v209
	v_add_f32_e32 v197, v197, v185
	s_nop 0
	v_permlane16_swap_b32_e32 v136, v196
	v_permlane16_swap_b32_e32 v137, v197
	v_add_f32_e32 v136, v136, v196
	v_add_f32_e32 v137, v137, v197
	v_fma_f32 v244, -v243, v241, v136
	v_fma_f32 v245, v243, v240, v137
	v_fma_f32 v240, v242, v240, v244
	v_fma_f32 v241, v242, v241, v245
	v_lshl_add_u64 v[116:117], v[116:117], 0, s[4:5]
	v_add_u32_e32 v20, 64, v20
	s_and_b64 vcc, exec, s[22:23]
	s_cbranch_vccnz .LBB0_702
	s_mov_b32 s24, s40
	s_waitcnt vmcnt(5)
	v_mov_b32_e32 v108, v118
	v_mov_b32_e32 v109, v119
	s_waitcnt vmcnt(4)
	v_mov_b32_e32 v112, v120
	v_mov_b32_e32 v113, v121
	s_waitcnt vmcnt(3)
	v_mov_b32_e32 v114, v122
	v_mov_b32_e32 v115, v123
	s_waitcnt vmcnt(2)
	v_mov_b32_e32 v110, v124
	v_mov_b32_e32 v111, v125
	s_branch .LBB0_671
